# w_in epilogue: the first copy of the rotary-key block also fetches its 16 rope-table entries up front
# baseline (speedup 1.0000x reference)
.LBB0_473:
	s_andn2_saveexec_b64 s[52:53], s[10:11]
	s_cbranch_execz .LBB0_539
	v_add_u32_e32 v136, 0xfffffd00, v128
	v_cmp_eq_u32_e64 s[10:11], 0, v136
	s_mov_b64 s[8:9], -1
	s_and_b64 vcc, exec, s[42:43]
	s_cbranch_vccnz .Lgi_rp1_skip
	v_lshlrev_b32_e32 v226, 2, v160
	v_bfe_u32 v227, v163, 6, 6
	v_cndmask_b32_e64 v228, v151, v227, s[10:11]
	v_lshl_or_b32 v228, v228, 7, v226
	global_load_dwordx2 v[194:195], v228, s[36:37]
	v_cndmask_b32_e64 v229, v159, v227, s[10:11]
	v_lshl_or_b32 v229, v229, 7, v226
	global_load_dwordx2 v[196:197], v229, s[36:37]
	v_cndmask_b32_e64 v228, v157, v227, s[10:11]
	v_lshl_or_b32 v228, v228, 7, v226
	global_load_dwordx2 v[198:199], v228, s[36:37]
	v_cndmask_b32_e64 v229, v156, v227, s[10:11]
	v_lshl_or_b32 v229, v229, 7, v226
	global_load_dwordx2 v[200:201], v229, s[36:37]
	v_cndmask_b32_e64 v228, v155, v227, s[10:11]
	v_lshl_or_b32 v228, v228, 7, v226
	global_load_dwordx2 v[202:203], v228, s[36:37]
	v_cndmask_b32_e64 v229, v154, v227, s[10:11]
	v_lshl_or_b32 v229, v229, 7, v226
	global_load_dwordx2 v[204:205], v229, s[36:37]
	v_cndmask_b32_e64 v228, v153, v227, s[10:11]
	v_lshl_or_b32 v228, v228, 7, v226
	global_load_dwordx2 v[206:207], v228, s[36:37]
	v_cndmask_b32_e64 v229, v152, v227, s[10:11]
	v_lshl_or_b32 v229, v229, 7, v226
	global_load_dwordx2 v[208:209], v229, s[36:37]
	v_cndmask_b32_e64 v228, v150, v227, s[10:11]
	v_lshl_or_b32 v228, v228, 7, v226
	global_load_dwordx2 v[210:211], v228, s[36:37]
	v_cndmask_b32_e64 v229, v149, v227, s[10:11]
	v_lshl_or_b32 v229, v229, 7, v226
	global_load_dwordx2 v[212:213], v229, s[36:37]
	v_cndmask_b32_e64 v228, v148, v227, s[10:11]
	v_lshl_or_b32 v228, v228, 7, v226
	global_load_dwordx2 v[214:215], v228, s[36:37]
	v_cndmask_b32_e64 v229, v147, v227, s[10:11]
	v_lshl_or_b32 v229, v229, 7, v226
	global_load_dwordx2 v[216:217], v229, s[36:37]
	v_cndmask_b32_e64 v228, v146, v227, s[10:11]
	v_lshl_or_b32 v228, v228, 7, v226
	global_load_dwordx2 v[218:219], v228, s[36:37]
	v_cndmask_b32_e64 v229, v145, v227, s[10:11]
	v_lshl_or_b32 v229, v229, 7, v226
	global_load_dwordx2 v[220:221], v229, s[36:37]
	v_cndmask_b32_e64 v228, v144, v227, s[10:11]
	v_lshl_or_b32 v228, v228, 7, v226
	global_load_dwordx2 v[222:223], v228, s[36:37]
	v_cndmask_b32_e64 v229, v135, v227, s[10:11]
	v_lshl_or_b32 v229, v229, 7, v226
	global_load_dwordx2 v[224:225], v229, s[36:37]
.Lgi_rp1_skip:
	s_and_b64 vcc, exec, s[42:43]
	s_cbranch_vccz .LBB0_476
	v_and_b32_e32 v140, 0xcc, v163
	s_mov_b64 s[8:9], 0
	v_mov_b32_e32 v139, v120
	v_mov_b32_e32 v133, v124
.LBB0_476:
	v_ashrrev_i32_e32 v134, 12, v158
	s_andn2_b64 vcc, exec, s[8:9]
	v_mov_b64_e32 v[142:143], v[132:133]
	s_cbranch_vccnz .LBB0_478
	v_bfe_u32 v133, v163, 6, 6
	v_cndmask_b32_e64 v133, v151, v133, s[10:11]
	v_lshlrev_b32_e32 v137, 2, v160
	v_lshl_or_b32 v133, v133, 7, v137
	v_and_b32_e32 v133, 0xfcc, v163
	v_add_u32_e32 v140, 0x100, v133
	s_waitcnt vmcnt(15)
	v_mov_b32_e32 v138, v194
	v_mov_b32_e32 v139, v195
	v_pk_mul_f32 v[142:143], v[120:121], v[138:139] op_sel:[0,1] op_sel_hi:[0,0]
	v_pk_mul_f32 v[168:169], v[124:125], v[138:139]
	v_pk_fma_f32 v[138:139], v[124:125], v[138:139], v[142:143] op_sel_hi:[0,1,1]
	v_sub_f32_e32 v133, v168, v142
	v_mov_b64_e32 v[142:143], v[134:135]

.LBB0_480:
	s_andn2_b64 vcc, exec, s[0:1]
	v_mov_b64_e32 v[140:141], v[132:133]
	s_cbranch_vccnz .LBB0_482
	v_bfe_u32 v138, v133, 6, 6
	v_cndmask_b32_e64 v138, v159, v138, s[10:11]
	v_lshlrev_b32_e32 v139, 2, v160
	v_lshl_or_b32 v138, v138, 7, v139
	v_and_b32_e32 v133, 0xfcd, v133
	v_add_u32_e32 v138, 0x100, v133
	s_waitcnt vmcnt(16)
	v_mov_b32_e32 v140, v196
	v_mov_b32_e32 v141, v197
	v_pk_mul_f32 v[120:121], v[120:121], v[140:141] op_sel:[1,0]
	v_pk_mul_f32 v[142:143], v[124:125], v[140:141] op_sel:[1,1] op_sel_hi:[1,0]
	v_pk_fma_f32 v[124:125], v[124:125], v[140:141], v[120:121] op_sel:[1,1,0] op_sel_hi:[1,0,1] neg_lo:[0,0,1] neg_hi:[0,0,1]
	v_add_f32_e32 v121, v142, v120
	v_mov_b64_e32 v[140:141], v[134:135]

.LBB0_484:
	s_andn2_b64 vcc, exec, s[0:1]
	v_mov_b64_e32 v[124:125], v[132:133]
	s_cbranch_vccnz .LBB0_486
	v_bfe_u32 v120, v121, 6, 6
	v_cndmask_b32_e64 v120, v157, v120, s[10:11]
	v_lshlrev_b32_e32 v124, 2, v160
	v_lshl_or_b32 v120, v120, 7, v124
	v_and_b32_e32 v120, 0xfce, v121
	v_add_u32_e32 v120, 0x100, v120
	s_waitcnt vmcnt(17)
	v_mov_b32_e32 v124, v198
	v_mov_b32_e32 v125, v199
	v_pk_mul_f32 v[138:139], v[122:123], v[124:125] op_sel_hi:[0,1]
	v_pk_mul_f32 v[140:141], v[126:127], v[124:125] op_sel:[0,1] op_sel_hi:[1,0]
	v_pk_fma_f32 v[142:143], v[126:127], v[124:125], v[138:139] op_sel:[0,1,0] op_sel_hi:[0,0,1] neg_lo:[0,0,1] neg_hi:[0,0,1]
	v_add_f32_e32 v122, v140, v138
	v_mov_b64_e32 v[124:125], v[134:135]
	v_mov_b32_e32 v126, v143

.LBB0_488:
	s_andn2_b64 vcc, exec, s[0:1]
	v_mov_b64_e32 v[124:125], v[132:133]
	s_cbranch_vccnz .LBB0_490
	v_bfe_u32 v120, v121, 6, 6
	v_cndmask_b32_e64 v120, v156, v120, s[10:11]
	v_lshlrev_b32_e32 v122, 2, v160
	v_lshl_or_b32 v120, v120, 7, v122
	v_mov_b32_e32 v122, v123
	v_mov_b32_e32 v126, v127
	v_and_b32_e32 v120, 0xfcf, v121
	v_add_u32_e32 v120, 0x100, v120
	s_waitcnt vmcnt(18)
	v_mov_b32_e32 v124, v200
	v_mov_b32_e32 v125, v201
	v_pk_mul_f32 v[122:123], v[122:123], v[124:125] op_sel_hi:[0,1]
	v_pk_mul_f32 v[138:139], v[126:127], v[124:125] op_sel:[0,1] op_sel_hi:[0,0]
	v_pk_fma_f32 v[126:127], v[126:127], v[124:125], v[122:123] op_sel:[0,1,0] op_sel_hi:[0,0,1] neg_lo:[0,0,1] neg_hi:[0,0,1]
	v_add_f32_e32 v123, v138, v122
	v_mov_b64_e32 v[124:125], v[134:135]

.LBB0_492:
	s_andn2_b64 vcc, exec, s[0:1]
	v_mov_b64_e32 v[124:125], v[132:133]
	s_cbranch_vccnz .LBB0_494
	v_bfe_u32 v120, v121, 6, 6
	v_cndmask_b32_e64 v120, v155, v120, s[10:11]
	v_lshlrev_b32_e32 v122, 2, v160
	v_lshl_or_b32 v120, v120, 7, v122
	v_and_b32_e32 v120, 0xfdc, v121
	v_add_u32_e32 v120, 0x100, v120
	s_waitcnt vmcnt(19)
	v_mov_b32_e32 v122, v202
	v_mov_b32_e32 v123, v203
	v_pk_mul_f32 v[124:125], v[112:113], v[122:123] op_sel_hi:[0,1]
	v_pk_mul_f32 v[126:127], v[116:117], v[122:123] op_sel:[0,1] op_sel_hi:[1,0]
	v_pk_fma_f32 v[122:123], v[116:117], v[122:123], v[124:125] op_sel:[0,1,0] op_sel_hi:[0,0,1] neg_lo:[0,0,1] neg_hi:[0,0,1]
	v_add_f32_e32 v122, v126, v124
	v_mov_b64_e32 v[124:125], v[134:135]

.LBB0_496:
	s_andn2_b64 vcc, exec, s[0:1]
	v_mov_b64_e32 v[122:123], v[132:133]
	s_cbranch_vccnz .LBB0_498
	v_bfe_u32 v120, v121, 6, 6
	v_cndmask_b32_e64 v120, v154, v120, s[10:11]
	v_lshlrev_b32_e32 v122, 2, v160
	v_lshl_or_b32 v120, v120, 7, v122
	v_and_b32_e32 v120, 0xfdd, v121
	v_add_u32_e32 v120, 0x100, v120
	s_waitcnt vmcnt(20)
	v_mov_b32_e32 v122, v204
	v_mov_b32_e32 v123, v205
	v_pk_mul_f32 v[112:113], v[112:113], v[122:123] op_sel:[1,0]
	v_pk_mul_f32 v[124:125], v[116:117], v[122:123] op_sel:[1,1] op_sel_hi:[1,0]
	v_pk_fma_f32 v[116:117], v[116:117], v[122:123], v[112:113] op_sel:[1,1,0] op_sel_hi:[1,0,1] neg_lo:[0,0,1] neg_hi:[0,0,1]
	v_add_f32_e32 v113, v124, v112
	v_mov_b64_e32 v[122:123], v[134:135]

.LBB0_500:
	s_andn2_b64 vcc, exec, s[0:1]
	v_mov_b64_e32 v[116:117], v[132:133]
	s_cbranch_vccnz .LBB0_502
	v_bfe_u32 v112, v113, 6, 6
	v_cndmask_b32_e64 v112, v153, v112, s[10:11]
	v_lshlrev_b32_e32 v116, 2, v160
	v_lshl_or_b32 v112, v112, 7, v116
	v_and_b32_e32 v112, 0xfde, v113
	v_add_u32_e32 v112, 0x100, v112
	s_waitcnt vmcnt(21)
	v_mov_b32_e32 v116, v206
	v_mov_b32_e32 v117, v207
	v_pk_mul_f32 v[120:121], v[114:115], v[116:117] op_sel_hi:[0,1]
	v_pk_mul_f32 v[122:123], v[118:119], v[116:117] op_sel:[0,1] op_sel_hi:[1,0]
	v_pk_fma_f32 v[124:125], v[118:119], v[116:117], v[120:121] op_sel:[0,1,0] op_sel_hi:[0,0,1] neg_lo:[0,0,1] neg_hi:[0,0,1]
	v_add_f32_e32 v114, v122, v120
	v_mov_b64_e32 v[116:117], v[134:135]
	v_mov_b32_e32 v118, v125

.LBB0_504:
	s_andn2_b64 vcc, exec, s[0:1]
	v_mov_b64_e32 v[116:117], v[132:133]
	s_cbranch_vccnz .LBB0_506
	v_bfe_u32 v112, v113, 6, 6
	v_cndmask_b32_e64 v112, v152, v112, s[10:11]
	v_lshlrev_b32_e32 v114, 2, v160
	v_lshl_or_b32 v112, v112, 7, v114
	v_mov_b32_e32 v114, v115
	v_mov_b32_e32 v118, v119
	v_and_b32_e32 v112, 0xfdf, v113
	v_add_u32_e32 v112, 0x100, v112
	s_waitcnt vmcnt(22)
	v_mov_b32_e32 v116, v208
	v_mov_b32_e32 v117, v209
	v_pk_mul_f32 v[114:115], v[114:115], v[116:117] op_sel_hi:[0,1]
	v_pk_mul_f32 v[120:121], v[118:119], v[116:117] op_sel:[0,1] op_sel_hi:[0,0]
	v_pk_fma_f32 v[118:119], v[118:119], v[116:117], v[114:115] op_sel:[0,1,0] op_sel_hi:[0,0,1] neg_lo:[0,0,1] neg_hi:[0,0,1]
	v_add_f32_e32 v115, v120, v114
	v_mov_b64_e32 v[116:117], v[134:135]

.LBB0_508:
	s_andn2_b64 vcc, exec, s[0:1]
	v_mov_b64_e32 v[116:117], v[132:133]
	s_cbranch_vccnz .LBB0_510
	v_bfe_u32 v112, v113, 6, 6
	v_cndmask_b32_e64 v112, v150, v112, s[10:11]
	v_lshlrev_b32_e32 v114, 2, v160
	v_lshl_or_b32 v112, v112, 7, v114
	v_and_b32_e32 v112, 0xfec, v113
	v_add_u32_e32 v112, 0x100, v112
	s_waitcnt vmcnt(23)
	v_mov_b32_e32 v114, v210
	v_mov_b32_e32 v115, v211
	v_pk_mul_f32 v[116:117], v[104:105], v[114:115] op_sel_hi:[0,1]
	v_pk_mul_f32 v[118:119], v[108:109], v[114:115] op_sel:[0,1] op_sel_hi:[1,0]
	v_pk_fma_f32 v[114:115], v[108:109], v[114:115], v[116:117] op_sel:[0,1,0] op_sel_hi:[0,0,1] neg_lo:[0,0,1] neg_hi:[0,0,1]
	v_add_f32_e32 v114, v118, v116
	v_mov_b64_e32 v[116:117], v[134:135]

.LBB0_512:
	s_andn2_b64 vcc, exec, s[0:1]
	v_mov_b64_e32 v[114:115], v[132:133]
	s_cbranch_vccnz .LBB0_514
	v_bfe_u32 v112, v113, 6, 6
	v_cndmask_b32_e64 v112, v149, v112, s[10:11]
	v_lshlrev_b32_e32 v114, 2, v160
	v_lshl_or_b32 v112, v112, 7, v114
	v_and_b32_e32 v112, 0xfed, v113
	v_add_u32_e32 v112, 0x100, v112
	s_waitcnt vmcnt(24)
	v_mov_b32_e32 v114, v212
	v_mov_b32_e32 v115, v213
	v_pk_mul_f32 v[104:105], v[104:105], v[114:115] op_sel:[1,0]
	v_pk_mul_f32 v[116:117], v[108:109], v[114:115] op_sel:[1,1] op_sel_hi:[1,0]
	v_pk_fma_f32 v[108:109], v[108:109], v[114:115], v[104:105] op_sel:[1,1,0] op_sel_hi:[1,0,1] neg_lo:[0,0,1] neg_hi:[0,0,1]
	v_add_f32_e32 v105, v116, v104
	v_mov_b64_e32 v[114:115], v[134:135]

.LBB0_516:
	s_andn2_b64 vcc, exec, s[0:1]
	v_mov_b64_e32 v[108:109], v[132:133]
	s_cbranch_vccnz .LBB0_518
	v_bfe_u32 v104, v105, 6, 6
	v_cndmask_b32_e64 v104, v148, v104, s[10:11]
	v_lshlrev_b32_e32 v108, 2, v160
	v_lshl_or_b32 v104, v104, 7, v108
	v_and_b32_e32 v104, 0xfee, v105
	v_add_u32_e32 v104, 0x100, v104
	s_waitcnt vmcnt(25)
	v_mov_b32_e32 v108, v214
	v_mov_b32_e32 v109, v215
	v_pk_mul_f32 v[112:113], v[106:107], v[108:109] op_sel_hi:[0,1]
	v_pk_mul_f32 v[114:115], v[110:111], v[108:109] op_sel:[0,1] op_sel_hi:[1,0]
	v_pk_fma_f32 v[116:117], v[110:111], v[108:109], v[112:113] op_sel:[0,1,0] op_sel_hi:[0,0,1] neg_lo:[0,0,1] neg_hi:[0,0,1]
	v_add_f32_e32 v106, v114, v112
	v_mov_b64_e32 v[108:109], v[134:135]
	v_mov_b32_e32 v110, v117

.LBB0_520:
	s_andn2_b64 vcc, exec, s[0:1]
	v_mov_b64_e32 v[108:109], v[132:133]
	s_cbranch_vccnz .LBB0_522
	v_bfe_u32 v104, v105, 6, 6
	v_cndmask_b32_e64 v104, v147, v104, s[10:11]
	v_lshlrev_b32_e32 v106, 2, v160
	v_lshl_or_b32 v104, v104, 7, v106
	v_mov_b32_e32 v106, v107
	v_mov_b32_e32 v110, v111
	v_and_b32_e32 v104, 0xfef, v105
	v_add_u32_e32 v104, 0x100, v104
	s_waitcnt vmcnt(26)
	v_mov_b32_e32 v108, v216
	v_mov_b32_e32 v109, v217
	v_pk_mul_f32 v[106:107], v[106:107], v[108:109] op_sel_hi:[0,1]
	v_pk_mul_f32 v[112:113], v[110:111], v[108:109] op_sel:[0,1] op_sel_hi:[0,0]
	v_pk_fma_f32 v[110:111], v[110:111], v[108:109], v[106:107] op_sel:[0,1,0] op_sel_hi:[0,0,1] neg_lo:[0,0,1] neg_hi:[0,0,1]
	v_add_f32_e32 v107, v112, v106
	v_mov_b64_e32 v[108:109], v[134:135]

.LBB0_524:
	s_andn2_b64 vcc, exec, s[0:1]
	v_mov_b64_e32 v[108:109], v[132:133]
	s_cbranch_vccnz .LBB0_526
	v_bfe_u32 v104, v105, 6, 6
	v_cndmask_b32_e64 v104, v146, v104, s[10:11]
	v_lshlrev_b32_e32 v106, 2, v160
	v_lshl_or_b32 v104, v104, 7, v106
	v_and_b32_e32 v104, 0xffc, v105
	v_add_u32_e32 v104, 0x100, v104
	s_waitcnt vmcnt(27)
	v_mov_b32_e32 v106, v218
	v_mov_b32_e32 v107, v219
	v_pk_mul_f32 v[108:109], v[96:97], v[106:107] op_sel_hi:[0,1]
	v_pk_mul_f32 v[110:111], v[100:101], v[106:107] op_sel:[0,1] op_sel_hi:[1,0]
	v_pk_fma_f32 v[106:107], v[100:101], v[106:107], v[108:109] op_sel:[0,1,0] op_sel_hi:[0,0,1] neg_lo:[0,0,1] neg_hi:[0,0,1]
	v_add_f32_e32 v106, v110, v108
	v_mov_b64_e32 v[108:109], v[134:135]

.LBB0_528:
	s_andn2_b64 vcc, exec, s[0:1]
	v_mov_b64_e32 v[106:107], v[132:133]
	s_cbranch_vccnz .LBB0_530
	v_bfe_u32 v104, v105, 6, 6
	v_cndmask_b32_e64 v104, v145, v104, s[10:11]
	v_lshlrev_b32_e32 v106, 2, v160
	v_lshl_or_b32 v104, v104, 7, v106
	v_and_b32_e32 v104, 0xffd, v105
	v_add_u32_e32 v104, 0x100, v104
	s_waitcnt vmcnt(28)
	v_mov_b32_e32 v106, v220
	v_mov_b32_e32 v107, v221
	v_pk_mul_f32 v[96:97], v[96:97], v[106:107] op_sel:[1,0]
	v_pk_mul_f32 v[108:109], v[100:101], v[106:107] op_sel:[1,1] op_sel_hi:[1,0]
	v_pk_fma_f32 v[100:101], v[100:101], v[106:107], v[96:97] op_sel:[1,1,0] op_sel_hi:[1,0,1] neg_lo:[0,0,1] neg_hi:[0,0,1]
	v_add_f32_e32 v97, v108, v96
	v_mov_b64_e32 v[106:107], v[134:135]

.LBB0_532:
	s_andn2_b64 vcc, exec, s[0:1]
	v_mov_b64_e32 v[100:101], v[132:133]
	s_cbranch_vccnz .LBB0_534
	v_bfe_u32 v96, v97, 6, 6
	v_cndmask_b32_e64 v96, v144, v96, s[10:11]
	v_lshlrev_b32_e32 v100, 2, v160
	v_lshl_or_b32 v96, v96, 7, v100
	v_and_b32_e32 v96, 0xffe, v97
	v_add_u32_e32 v96, 0x100, v96
	s_waitcnt vmcnt(29)
	v_mov_b32_e32 v100, v222
	v_mov_b32_e32 v101, v223
	v_pk_mul_f32 v[104:105], v[98:99], v[100:101] op_sel_hi:[0,1]
	v_pk_mul_f32 v[106:107], v[102:103], v[100:101] op_sel:[0,1] op_sel_hi:[1,0]
	v_pk_fma_f32 v[108:109], v[102:103], v[100:101], v[104:105] op_sel:[0,1,0] op_sel_hi:[0,0,1] neg_lo:[0,0,1] neg_hi:[0,0,1]
	v_add_f32_e32 v98, v106, v104
	v_mov_b64_e32 v[100:101], v[134:135]
	v_mov_b32_e32 v102, v109

.LBB0_536:
	s_andn2_b64 vcc, exec, s[0:1]
	s_cbranch_vccnz .LBB0_538
	v_bfe_u32 v96, v97, 6, 6
	v_cndmask_b32_e64 v96, v135, v96, s[10:11]
	v_lshlrev_b32_e32 v98, 2, v160
	v_lshl_or_b32 v96, v96, 7, v98
	v_mov_b32_e32 v98, v99
	v_mov_b32_e32 v102, v103
	v_and_b32_e32 v96, 0xfff, v97
	v_add_u32_e32 v96, 0x100, v96
	v_mov_b64_e32 v[132:133], v[134:135]
	s_waitcnt vmcnt(30)
	v_mov_b32_e32 v100, v224
	v_mov_b32_e32 v101, v225
	v_pk_mul_f32 v[98:99], v[98:99], v[100:101] op_sel_hi:[0,1]
	v_pk_mul_f32 v[104:105], v[102:103], v[100:101] op_sel:[0,1] op_sel_hi:[0,0]
	v_pk_fma_f32 v[102:103], v[102:103], v[100:101], v[98:99] op_sel:[0,1,0] op_sel_hi:[0,0,1] neg_lo:[0,0,1] neg_hi:[0,0,1]
	v_add_f32_e32 v99, v104, v98
